# all eight GEMM K-loops peeled (FFN-up loops too): no accumulator zeroing, first two waits relaxed
# baseline (speedup 1.0000x reference)
; #define PG8_STAGE(bufoff, gbase, voff) do { _Pragma("unroll") for (int _i = 0; _i < 2; ++_i) \
;         __builtin_amdgcn_global_load_lds((const unsigned*)((const char*)(gbase) + (voff)[_i]), (PG8_LAS unsigned*)(lds + (bufoff) + ldsw + _i * 8192), 16, 0, 0); } while (0)
; #define PG8_WAIT_V(n) asm volatile("s_waitcnt vmcnt(" #n ")" ::: "memory")
; #define PG8_BAR __builtin_amdgcn_s_barrier()
; template <class Epi, class Sched, bool ALIGN_EPI = false, bool SP2 = false>
; __device__ __forceinline__ void gemm_phase(PG8_LAS unsigned char* lds, const Gemm g, const Sched& S, const Epi& E) {
;     ...
;     if constexpr (SP2) {
;         PG8_STAGE(PG8_SB(0, 0), cB, voffB); PG8_STAGE(PG8_SB(0, 1), cB + hstepB, voffB); PG8_STAGE(PG8_SA(0, 0), cA, voffA); PG8_STAGE(PG8_SA(0, 1), cA + hstepA, voffA);
;         if (wr == 1) PG8_BAR;
;         PG8_WAIT_V(2); PG8_BAR;
;         PG8_STAGE(PG8_SB(1, 0), cB + kstep, voffB); PG8_STAGE(PG8_SA(1, 0), cA + kstepA, voffA); PG8_STAGE(PG8_SB(1, 1), cB + hstepB + kstep, voffB);
;         PG8_WAIT_V(6); PG8_BAR;
.LBB0_484:
	s_mov_b64 s[56:57], 0x80
	s_and_b32 s1, s2, 3
	s_add_i32 m0, s91, 0x18000
	v_lshl_add_u64 v[6:7], v[6:7], 0, s[56:57]
	s_lshl_b32 s3, s0, 13
	s_lshl_b32 s96, s1, 5
	s_lshl_b32 s1, s1, 12
	s_waitcnt vmcnt(2)
	s_barrier
	global_load_lds_dwordx4 v[6:7], off
	v_lshl_add_u64 v[4:5], v[4:5], 0, s[56:57]
	s_add_i32 m0, s91, 0x1a000
	s_add_i32 s97, s91, 0x8000
	s_add_i32 s9, s91, 0xa000
	global_load_lds_dwordx4 v[4:5], off
	v_lshl_add_u64 v[0:1], v[0:1], 0, s[56:57]
	s_mov_b32 m0, s97
	s_add_u32 s6, s82, 0x40080
	global_load_lds_dwordx4 v[0:1], off
	v_lshl_add_u64 v[0:1], v[2:3], 0, s[56:57]
	s_mov_b32 m0, s9
	s_addc_u32 s7, s83, 0
	global_load_lds_dwordx4 v[0:1], off
	s_add_i32 m0, s91, 0x1c000
	v_lshl_add_u64 v[0:1], s[6:7], 0, v[130:131]
	global_load_lds_dwordx4 v[0:1], off
	v_lshl_add_u64 v[0:1], s[6:7], 0, v[134:135]
	s_add_i32 m0, s91, 0x1e000
	s_cmpk_lt_u32 s4, 0x100
	global_load_lds_dwordx4 v[0:1], off
	v_lshrrev_b32_e32 v0, 1, v8
	v_and_b32_e32 v0, 24, v0
	v_and_b32_e32 v1, 15, v8
	v_lshlrev_b32_e32 v2, 1, v0
	v_lshl_or_b32 v138, s0, 6, v1
	v_lshl_or_b32 v1, v1, 6, v2
	v_lshlrev_b32_e32 v2, 2, v8
	v_and_b32_e32 v2, 32, v2
	s_waitcnt vmcnt(0)
	s_cselect_b64 s[58:59], -1, 0
	s_lshl_b32 s2, s2, 13
	v_bitop3_b32 v3, v1, s3, v2 bitop3:0xde
	s_and_b32 s2, s2, 0x2000
	v_ashrrev_i32_e32 v139, 31, v138
	s_sext_i32_i8 s18, s5
	v_bitop3_b32 v147, v1, s1, v2 bitop3:0xde
	v_cmp_gt_u32_e64 s[0:1], 64, v238
	v_lshlrev_b64 v[140:141], 6, v[138:139]
	s_ashr_i32 s12, s10, 31
	s_mov_b32 s13, s10
	v_mov_b64_e32 v[142:143], 0x440
	v_mov_b64_e32 v[144:145], 0x43f
	s_add_i32 s14, 0, 0x10000
	s_add_i32 s15, 0, 0x14000
	v_add_u32_e32 v139, 0, v3
	v_mov_b32_e32 v149, 0x358637bd
	s_lshl_b32 s16, s2, 1
	v_lshlrev_b32_e32 v136, 1, v0
	s_mov_b32 s17, 0
	s_barrier
	s_branch .LBB0_487

;     __host__ __device__ __forceinline__ bool next(int i, Unit& u) const { const long L = (long)i * G + c; if (L >= nwg) return false; map((int)L, u); return true; }
; #define PG8_STAGE(bufoff, gbase, voff) do { _Pragma("unroll") for (int _i = 0; _i < 2; ++_i) \
;         __builtin_amdgcn_global_load_lds((const unsigned*)((const char*)(gbase) + (voff)[_i]), (PG8_LAS unsigned*)(lds + (bufoff) + ldsw + _i * 8192), 16, 0, 0); } while (0)
; #define PG8_LDA(dst, b, h) do { _Pragma("unroll") for (int m = 0; m < 4; ++m) _Pragma("unroll") for (int k = 0; k < 2; ++k) dst[m][k] = *(const PG8_LAS bf16x8*)(lds + PG8_SA(b, h) + aoff + m * 2048 + k * 1024); } while (0)
; #define PG8_WAIT_V(n) asm volatile("s_waitcnt vmcnt(" #n ")" ::: "memory")
; #define PG8_BAR __builtin_amdgcn_s_barrier()
; template <class Epi, class Sched, bool ALIGN_EPI = false, bool SP2 = false>
; __device__ __forceinline__ void gemm_phase(PG8_LAS unsigned char* lds, const Gemm g, const Sched& S, const Epi& E) {
;     ...
;         const bool has_next = S.next(ui + 1, nxt);
;         const char* nA = has_next ? (const char*)g.A + (size_t)nxt.pm * tstepA + (size_t)(nxt.k0 >> 6) * kstepA + (nxt.qa > 0 ? hstepA : (size_t)0) : cA; const char* nB = has_next ? (const char*)g.Bt + (size_t)nxt.pn * tstepB + (size_t)nxt.k0 * 2 + (nxt.qb > 0 ? hstepB : (size_t)0) : cB;
;         const bool whole = cur.qa < 0;
;         const int nt = cur.nt;
;         for (int t = 0; t < nt; t += 2) {
;             const bool last = (t == nt - 2);
;             const char* a1 = cA + (size_t)(t + 1) * kstepA;
;             const char* a2 = last ? nA : cA + (size_t)(t + 2) * kstepA; const char* b2 = last ? nB : cB + (size_t)(t + 2) * kstep;
;             const char* a3 = a2 + kstepA; const char* b3 = b2 + kstep;
;             if (last && has_next) S.a_ready(nxt);
;             if constexpr (SP2) {
;             PG8_LDB(B0, 0, 0); PG8_LDB(B1, 0, 1); PG8_SCHED; PG8_LDA(At, 0, 0); PG8_STAGE(PG8_SA(1, 1), a1 + hstepA, voffA);
;             PG8_WAIT_V(8); PG8_WAIT_L(0); PG8_BAR; PG8_MMA(0, 0, At, B0); if (whole) PG8_MMA(0, 1, At, B1); PG8_BAR; PG8_SCHED;
;             PG8_LDA(At, 0, 1); PG8_STAGE(PG8_SB(0, 0), b2, voffB); PG8_STAGE(PG8_SB(0, 1), b2 + hstepB, voffB); PG8_STAGE(PG8_SA(0, 0), a2, voffA);
;             PG8_WAIT_V(8); PG8_WAIT_L(0); PG8_BAR; if (whole) { PG8_MMA(1, 0, At, B0); PG8_MMA(1, 1, At, B1); } PG8_BAR; PG8_SCHED;
.LBB0_489:
	s_ashr_i32 s63, s62, 31
	s_lshl_b64 s[6:7], s[62:63], 19
	s_add_u32 s64, s30, s6
	s_addc_u32 s65, s31, s7
	s_and_b64 s[6:7], exec, s[4:5]
	s_cselect_b32 s19, s81, s65
	s_cselect_b32 s20, s80, s64
	s_ashr_i32 s61, s60, 31
	s_lshl_b64 s[6:7], s[60:61], 19
	s_add_u32 s76, s38, s6
	s_addc_u32 s77, s39, s7
	s_and_b64 s[6:7], exec, s[4:5]
	s_cselect_b32 s21, s83, s77
	s_cselect_b32 s22, s82, s76
	s_cmp_lt_i32 s62, 64
	s_mov_b32 s23, 0
	s_cselect_b64 s[84:85], -1, 0
	s_mov_b64 s[6:7], -1
	s_or_b32 s52, s23, 1
	s_lshl_b64 s[24:25], s[52:53], 7
	s_add_u32 s28, s80, s24
	v_add_u32_e32 v146, s14, v147
	s_addc_u32 s29, s81, s25
	s_add_i32 s52, s23, 2
	ds_read_b128 v[150:153], v146
	ds_read_b128 v[154:157], v146 offset:1024
	ds_read_b128 v[158:161], v146 offset:2048
	ds_read_b128 v[162:165], v146 offset:3072
	v_add_u32_e32 v146, s15, v147
	s_lshl_b64 s[24:25], s[52:53], 7
	ds_read_b128 v[166:169], v146
	ds_read_b128 v[170:173], v146 offset:1024
	ds_read_b128 v[174:177], v146 offset:2048
	ds_read_b128 v[178:181], v146 offset:3072
	s_add_u32 s61, s80, s24
	s_addc_u32 s63, s81, s25
	s_and_b64 s[26:27], s[6:7], exec
	s_cselect_b32 s87, s63, s19
	s_cselect_b32 s86, s61, s20
	s_add_u32 s24, s82, s24
	s_addc_u32 s25, s83, s25
	s_and_b64 s[6:7], s[6:7], exec
	s_cselect_b32 s7, s25, s21
	s_cselect_b32 s6, s24, s22
	s_add_u32 s24, s28, 0x40000
	s_addc_u32 s25, s29, 0
	v_lshl_add_u64 v[214:215], s[24:25], 0, v[128:129]
	s_add_i32 m0, s91, 0xc000
	ds_read_b128 v[182:185], v139
	ds_read_b128 v[186:189], v139 offset:1024
	ds_read_b128 v[190:193], v139 offset:2048
	ds_read_b128 v[194:197], v139 offset:3072
	ds_read_b128 v[198:201], v139 offset:4096
	ds_read_b128 v[202:205], v139 offset:5120
	ds_read_b128 v[206:209], v139 offset:6144
	ds_read_b128 v[210:213], v139 offset:7168
	global_load_lds_dwordx4 v[214:215], off
	v_lshl_add_u64 v[214:215], s[24:25], 0, v[132:133]
	s_add_i32 m0, s91, 0xe000
	s_nop 0
	global_load_lds_dwordx4 v[214:215], off
	s_waitcnt vmcnt(16)
	s_waitcnt lgkmcnt(0)
	s_barrier
	s_setprio 1
	s_waitcnt lgkmcnt(0)
	v_mfma_f32_16x16x32_bf16 v[124:127], v[150:153], v[182:185], 0
	v_mfma_f32_16x16x32_bf16 v[120:123], v[158:161], v[182:185], 0
	v_mfma_f32_16x16x32_bf16 v[108:111], v[150:153], v[190:193], 0
	v_mfma_f32_16x16x32_bf16 v[104:107], v[158:161], v[190:193], 0
	v_mfma_f32_16x16x32_bf16 v[92:95], v[150:153], v[198:201], 0
	v_mfma_f32_16x16x32_bf16 v[88:91], v[158:161], v[198:201], 0
	v_mfma_f32_16x16x32_bf16 v[76:79], v[150:153], v[206:209], 0
	v_mfma_f32_16x16x32_bf16 v[72:75], v[158:161], v[206:209], 0
	v_mfma_f32_16x16x32_bf16 v[124:127], v[154:157], v[186:189], v[124:127]
	v_mfma_f32_16x16x32_bf16 v[120:123], v[162:165], v[186:189], v[120:123]
	v_mfma_f32_16x16x32_bf16 v[108:111], v[154:157], v[194:197], v[108:111]
	v_mfma_f32_16x16x32_bf16 v[104:107], v[162:165], v[194:197], v[104:107]
	v_mfma_f32_16x16x32_bf16 v[92:95], v[154:157], v[202:205], v[92:95]
	v_mfma_f32_16x16x32_bf16 v[88:91], v[162:165], v[202:205], v[88:91]
	v_mfma_f32_16x16x32_bf16 v[76:79], v[154:157], v[210:213], v[76:79]
	v_mfma_f32_16x16x32_bf16 v[72:75], v[162:165], v[210:213], v[72:75]
	s_setprio 0
	s_setprio 1
	v_mfma_f32_16x16x32_bf16 v[116:119], v[166:169], v[182:185], 0
	v_mfma_f32_16x16x32_bf16 v[112:115], v[174:177], v[182:185], 0
	v_mfma_f32_16x16x32_bf16 v[100:103], v[166:169], v[190:193], 0
	v_mfma_f32_16x16x32_bf16 v[96:99], v[174:177], v[190:193], 0
	v_mfma_f32_16x16x32_bf16 v[84:87], v[166:169], v[198:201], 0
	v_mfma_f32_16x16x32_bf16 v[80:83], v[174:177], v[198:201], 0
	v_mfma_f32_16x16x32_bf16 v[68:71], v[166:169], v[206:209], 0
	v_mfma_f32_16x16x32_bf16 v[64:67], v[174:177], v[206:209], 0
	v_mfma_f32_16x16x32_bf16 v[116:119], v[170:173], v[186:189], v[116:119]
	v_mfma_f32_16x16x32_bf16 v[112:115], v[178:181], v[186:189], v[112:115]
	v_mfma_f32_16x16x32_bf16 v[100:103], v[170:173], v[194:197], v[100:103]
	v_mfma_f32_16x16x32_bf16 v[96:99], v[178:181], v[194:197], v[96:99]
	v_mfma_f32_16x16x32_bf16 v[84:87], v[170:173], v[202:205], v[84:87]
	v_mfma_f32_16x16x32_bf16 v[80:83], v[178:181], v[202:205], v[80:83]
	v_mfma_f32_16x16x32_bf16 v[68:71], v[170:173], v[210:213], v[68:71]
	v_mfma_f32_16x16x32_bf16 v[64:67], v[178:181], v[210:213], v[64:67]
	s_setprio 0
	s_barrier
	s_add_i32 s24, s14, s90
	v_lshl_add_u64 v[214:215], s[6:7], 0, v[130:131]
	s_mov_b32 m0, s24
	ds_read_b128 v[182:185], v139 offset:16384
	ds_read_b128 v[186:189], v139 offset:17408
	ds_read_b128 v[190:193], v139 offset:18432
	ds_read_b128 v[194:197], v139 offset:19456
	ds_read_b128 v[198:201], v139 offset:20480
	ds_read_b128 v[202:205], v139 offset:21504
	ds_read_b128 v[206:209], v139 offset:22528
	ds_read_b128 v[210:213], v139 offset:23552
	global_load_lds_dwordx4 v[214:215], off
	s_add_i32 m0, s24, 0x2000
	s_add_u32 s24, s6, 0x40000
	v_lshl_add_u64 v[216:217], s[6:7], 0, v[134:135]
	s_addc_u32 s25, s7, 0
	s_add_i32 s26, s15, s90
	global_load_lds_dwordx4 v[216:217], off
	v_lshl_add_u64 v[218:219], s[24:25], 0, v[130:131]
	s_mov_b32 m0, s26
	v_lshl_add_u64 v[220:221], s[86:87], 0, v[132:133]
	global_load_lds_dwordx4 v[218:219], off
	v_lshl_add_u64 v[218:219], s[24:25], 0, v[134:135]
	s_add_i32 m0, s26, 0x2000
	s_nop 0
	global_load_lds_dwordx4 v[218:219], off
	v_lshl_add_u64 v[218:219], s[86:87], 0, v[128:129]
	s_mov_b32 m0, s91
	s_nop 0
	global_load_lds_dwordx4 v[218:219], off
	s_mov_b32 m0, s92
	s_nop 0
	global_load_lds_dwordx4 v[220:221], off
	s_waitcnt vmcnt(16)
	s_waitcnt lgkmcnt(0)
	s_barrier
; #define PG8_STAGE(bufoff, gbase, voff) do { _Pragma("unroll") for (int _i = 0; _i < 2; ++_i) \
;         __builtin_amdgcn_global_load_lds((const unsigned*)((const char*)(gbase) + (voff)[_i]), (PG8_LAS unsigned*)(lds + (bufoff) + ldsw + _i * 8192), 16, 0, 0); } while (0)
; #define PG8_LDA(dst, b, h) do { _Pragma("unroll") for (int m = 0; m < 4; ++m) _Pragma("unroll") for (int k = 0; k < 2; ++k) dst[m][k] = *(const PG8_LAS bf16x8*)(lds + PG8_SA(b, h) + aoff + m * 2048 + k * 1024); } while (0)
; #define PG8_LDB(dst, b, h) do { _Pragma("unroll") for (int n = 0; n < 2; ++n) _Pragma("unroll") for (int k = 0; k < 2; ++k) dst[n][k] = *(const PG8_LAS bf16x8*)(lds + PG8_SB(b, h) + boff + n * 2048 + k * 1024); } while (0)
; #define PG8_MMA(ai, bj, At, Bt) do { __builtin_amdgcn_s_setprio(1); _Pragma("unroll") for (int m = 0; m < 4; ++m) _Pragma("unroll") for (int n = 0; n < 2; ++n) _Pragma("unroll") for (int k = 0; k < 2; ++k) \
;         acc[ai][bj][m][n] = __builtin_amdgcn_mfma_f32_16x16x32_bf16(Bt[n][k], At[m][k], acc[ai][bj][m][n], 0, 0, 0); __builtin_amdgcn_s_setprio(0); } while (0)
; #define PG8_WAIT_V(n) asm volatile("s_waitcnt vmcnt(" #n ")" ::: "memory")
; #define PG8_WAIT_L(n) asm volatile("s_waitcnt lgkmcnt(" #n ")" ::: "memory")
; #define PG8_BAR __builtin_amdgcn_s_barrier()
; #define PG8_SCHED __builtin_amdgcn_sched_barrier(0)
; template <class Epi, class Sched, bool ALIGN_EPI = false, bool SP2 = false>
; __device__ __forceinline__ void gemm_phase(PG8_LAS unsigned char* lds, const Gemm g, const Sched& S, const Epi& E) {
;     ...
;             PG8_WAIT_V(8); PG8_WAIT_L(0); PG8_BAR; if (whole) { PG8_MMA(1, 0, At, B0); PG8_MMA(1, 1, At, B1); } PG8_BAR; PG8_SCHED;
;             PG8_LDB(B0, 1, 0); PG8_LDB(B1, 1, 1); PG8_SCHED; PG8_LDA(At, 1, 0); PG8_STAGE(PG8_SA(0, 1), a2 + hstepA, voffA);
;             PG8_WAIT_V(8); PG8_WAIT_L(0); PG8_BAR; PG8_MMA(0, 0, At, B0); if (whole) PG8_MMA(0, 1, At, B1); PG8_BAR; PG8_SCHED;
	s_setprio 1
	s_waitcnt lgkmcnt(0)
	v_mfma_f32_16x16x32_bf16 v[60:63], v[150:153], v[182:185], 0
	v_mfma_f32_16x16x32_bf16 v[56:59], v[158:161], v[182:185], 0
	v_mfma_f32_16x16x32_bf16 v[44:47], v[150:153], v[190:193], 0
	v_mfma_f32_16x16x32_bf16 v[40:43], v[158:161], v[190:193], 0
	v_mfma_f32_16x16x32_bf16 v[28:31], v[150:153], v[198:201], 0
	v_mfma_f32_16x16x32_bf16 v[24:27], v[158:161], v[198:201], 0
	v_mfma_f32_16x16x32_bf16 v[12:15], v[150:153], v[206:209], 0
	v_mfma_f32_16x16x32_bf16 v[8:11], v[158:161], v[206:209], 0
	v_mfma_f32_16x16x32_bf16 v[60:63], v[154:157], v[186:189], v[60:63]
	v_mfma_f32_16x16x32_bf16 v[56:59], v[162:165], v[186:189], v[56:59]
	v_mfma_f32_16x16x32_bf16 v[44:47], v[154:157], v[194:197], v[44:47]
	v_mfma_f32_16x16x32_bf16 v[40:43], v[162:165], v[194:197], v[40:43]
	v_mfma_f32_16x16x32_bf16 v[28:31], v[154:157], v[202:205], v[28:31]
	v_mfma_f32_16x16x32_bf16 v[24:27], v[162:165], v[202:205], v[24:27]
	v_mfma_f32_16x16x32_bf16 v[12:15], v[154:157], v[210:213], v[12:15]
	v_mfma_f32_16x16x32_bf16 v[8:11], v[162:165], v[210:213], v[8:11]
	s_setprio 0
	s_setprio 1
	v_mfma_f32_16x16x32_bf16 v[52:55], v[166:169], v[182:185], 0
	v_mfma_f32_16x16x32_bf16 v[48:51], v[174:177], v[182:185], 0
	v_mfma_f32_16x16x32_bf16 v[36:39], v[166:169], v[190:193], 0
	v_mfma_f32_16x16x32_bf16 v[32:35], v[174:177], v[190:193], 0
	v_mfma_f32_16x16x32_bf16 v[20:23], v[166:169], v[198:201], 0
	v_mfma_f32_16x16x32_bf16 v[16:19], v[174:177], v[198:201], 0
	v_mfma_f32_16x16x32_bf16 v[4:7], v[166:169], v[206:209], 0
	v_mfma_f32_16x16x32_bf16 v[0:3], v[174:177], v[206:209], 0
	v_mfma_f32_16x16x32_bf16 v[52:55], v[170:173], v[186:189], v[52:55]
	v_mfma_f32_16x16x32_bf16 v[48:51], v[178:181], v[186:189], v[48:51]
	v_mfma_f32_16x16x32_bf16 v[36:39], v[170:173], v[194:197], v[36:39]
	v_mfma_f32_16x16x32_bf16 v[32:35], v[178:181], v[194:197], v[32:35]
	v_mfma_f32_16x16x32_bf16 v[20:23], v[170:173], v[202:205], v[20:23]
	v_mfma_f32_16x16x32_bf16 v[16:19], v[178:181], v[202:205], v[16:19]
	v_mfma_f32_16x16x32_bf16 v[4:7], v[170:173], v[210:213], v[4:7]
	v_mfma_f32_16x16x32_bf16 v[0:3], v[178:181], v[210:213], v[0:3]
	s_setprio 0
	s_barrier
	s_add_i32 s26, 0, 0x18000
	v_add_u32_e32 v146, s26, v147
	s_add_i32 s27, 0, 0x1c000
	ds_read_b128 v[150:153], v146
	ds_read_b128 v[154:157], v146 offset:1024
	ds_read_b128 v[158:161], v146 offset:2048
	ds_read_b128 v[162:165], v146 offset:3072
	v_add_u32_e32 v146, s27, v147
	ds_read_b128 v[166:169], v146
	ds_read_b128 v[170:173], v146 offset:1024
	ds_read_b128 v[174:177], v146 offset:2048
	ds_read_b128 v[178:181], v146 offset:3072
	s_add_u32 s24, s86, 0x40000
	s_addc_u32 s25, s87, 0
	s_mov_b32 m0, s93
	v_lshl_add_u64 v[222:223], s[24:25], 0, v[128:129]
	ds_read_b128 v[182:185], v139 offset:32768
	ds_read_b128 v[186:189], v139 offset:33792
	ds_read_b128 v[190:193], v139 offset:34816
	ds_read_b128 v[194:197], v139 offset:35840
	ds_read_b128 v[198:201], v139 offset:36864
	ds_read_b128 v[202:205], v139 offset:37888
	ds_read_b128 v[206:209], v139 offset:38912
	ds_read_b128 v[210:213], v139 offset:39936
	global_load_lds_dwordx4 v[222:223], off
	v_lshl_add_u64 v[222:223], s[24:25], 0, v[132:133]
	s_mov_b32 m0, s94
	s_nop 0
	global_load_lds_dwordx4 v[222:223], off
	s_waitcnt vmcnt(8)
	s_waitcnt lgkmcnt(0)
	s_barrier
	s_setprio 1
	s_waitcnt lgkmcnt(0)
	v_mfma_f32_16x16x32_bf16 v[124:127], v[150:153], v[182:185], v[124:127]
	v_mfma_f32_16x16x32_bf16 v[120:123], v[158:161], v[182:185], v[120:123]
	v_mfma_f32_16x16x32_bf16 v[108:111], v[150:153], v[190:193], v[108:111]
	v_mfma_f32_16x16x32_bf16 v[104:107], v[158:161], v[190:193], v[104:107]
	v_mfma_f32_16x16x32_bf16 v[92:95], v[150:153], v[198:201], v[92:95]
	v_mfma_f32_16x16x32_bf16 v[88:91], v[158:161], v[198:201], v[88:91]
	v_mfma_f32_16x16x32_bf16 v[76:79], v[150:153], v[206:209], v[76:79]
	v_mfma_f32_16x16x32_bf16 v[72:75], v[158:161], v[206:209], v[72:75]
	v_mfma_f32_16x16x32_bf16 v[124:127], v[154:157], v[186:189], v[124:127]
	v_mfma_f32_16x16x32_bf16 v[120:123], v[162:165], v[186:189], v[120:123]
	v_mfma_f32_16x16x32_bf16 v[108:111], v[154:157], v[194:197], v[108:111]
	v_mfma_f32_16x16x32_bf16 v[104:107], v[162:165], v[194:197], v[104:107]
	v_mfma_f32_16x16x32_bf16 v[92:95], v[154:157], v[202:205], v[92:95]
	v_mfma_f32_16x16x32_bf16 v[88:91], v[162:165], v[202:205], v[88:91]
	v_mfma_f32_16x16x32_bf16 v[76:79], v[154:157], v[210:213], v[76:79]
	v_mfma_f32_16x16x32_bf16 v[72:75], v[162:165], v[210:213], v[72:75]
	s_setprio 0
	s_setprio 1
	v_mfma_f32_16x16x32_bf16 v[116:119], v[166:169], v[182:185], v[116:119]
	v_mfma_f32_16x16x32_bf16 v[112:115], v[174:177], v[182:185], v[112:115]
	v_mfma_f32_16x16x32_bf16 v[100:103], v[166:169], v[190:193], v[100:103]
	v_mfma_f32_16x16x32_bf16 v[96:99], v[174:177], v[190:193], v[96:99]
	v_mfma_f32_16x16x32_bf16 v[84:87], v[166:169], v[198:201], v[84:87]
	v_mfma_f32_16x16x32_bf16 v[80:83], v[174:177], v[198:201], v[80:83]
	v_mfma_f32_16x16x32_bf16 v[68:71], v[166:169], v[206:209], v[68:71]
	v_mfma_f32_16x16x32_bf16 v[64:67], v[174:177], v[206:209], v[64:67]
	v_mfma_f32_16x16x32_bf16 v[116:119], v[170:173], v[186:189], v[116:119]
	v_mfma_f32_16x16x32_bf16 v[112:115], v[178:181], v[186:189], v[112:115]
	v_mfma_f32_16x16x32_bf16 v[100:103], v[170:173], v[194:197], v[100:103]
	v_mfma_f32_16x16x32_bf16 v[96:99], v[178:181], v[194:197], v[96:99]
	v_mfma_f32_16x16x32_bf16 v[84:87], v[170:173], v[202:205], v[84:87]
	v_mfma_f32_16x16x32_bf16 v[80:83], v[178:181], v[202:205], v[80:83]
	v_mfma_f32_16x16x32_bf16 v[68:71], v[170:173], v[210:213], v[68:71]
	v_mfma_f32_16x16x32_bf16 v[64:67], v[178:181], v[210:213], v[64:67]
	s_setprio 0
	s_barrier
; #define PG8_STAGE(bufoff, gbase, voff) do { _Pragma("unroll") for (int _i = 0; _i < 2; ++_i) \
;         __builtin_amdgcn_global_load_lds((const unsigned*)((const char*)(gbase) + (voff)[_i]), (PG8_LAS unsigned*)(lds + (bufoff) + ldsw + _i * 8192), 16, 0, 0); } while (0)
; #define PG8_LDA(dst, b, h) do { _Pragma("unroll") for (int m = 0; m < 4; ++m) _Pragma("unroll") for (int k = 0; k < 2; ++k) dst[m][k] = *(const PG8_LAS bf16x8*)(lds + PG8_SA(b, h) + aoff + m * 2048 + k * 1024); } while (0)
; #define PG8_MMA(ai, bj, At, Bt) do { __builtin_amdgcn_s_setprio(1); _Pragma("unroll") for (int m = 0; m < 4; ++m) _Pragma("unroll") for (int n = 0; n < 2; ++n) _Pragma("unroll") for (int k = 0; k < 2; ++k) \
;         acc[ai][bj][m][n] = __builtin_amdgcn_mfma_f32_16x16x32_bf16(Bt[n][k], At[m][k], acc[ai][bj][m][n], 0, 0, 0); __builtin_amdgcn_s_setprio(0); } while (0)
; #define PG8_WAIT_V(n) asm volatile("s_waitcnt vmcnt(" #n ")" ::: "memory")
; #define PG8_WAIT_L(n) asm volatile("s_waitcnt lgkmcnt(" #n ")" ::: "memory")
; #define PG8_BAR __builtin_amdgcn_s_barrier()
; #define PG8_SCHED __builtin_amdgcn_sched_barrier(0)
; template <class Epi, class Sched, bool ALIGN_EPI = false, bool SP2 = false>
; __device__ __forceinline__ void gemm_phase(PG8_LAS unsigned char* lds, const Gemm g, const Sched& S, const Epi& E) {
;     ...
;             PG8_LDA(At, 1, 1); PG8_STAGE(PG8_SB(1, 0), b3, voffB); PG8_STAGE(PG8_SB(1, 1), b3 + hstepB, voffB); PG8_STAGE(PG8_SA(1, 0), a3, voffA);
;             PG8_WAIT_V(8); PG8_WAIT_L(0); PG8_BAR; if (whole) { PG8_MMA(1, 0, At, B0); PG8_MMA(1, 1, At, B1); } PG8_BAR; PG8_SCHED;
	s_add_i32 s24, s26, s90
	v_lshl_add_u64 v[214:215], v[214:215], 0, s[56:57]
	s_mov_b32 m0, s24
	ds_read_b128 v[182:185], v139 offset:49152
	ds_read_b128 v[186:189], v139 offset:50176
	ds_read_b128 v[190:193], v139 offset:51200
	ds_read_b128 v[194:197], v139 offset:52224
	ds_read_b128 v[198:201], v139 offset:53248
	ds_read_b128 v[202:205], v139 offset:54272
	ds_read_b128 v[206:209], v139 offset:55296
	ds_read_b128 v[210:213], v139 offset:56320
	global_load_lds_dwordx4 v[214:215], off
	s_add_i32 m0, s24, 0x2000
	s_add_u32 s6, s6, 0x40080
	v_lshl_add_u64 v[214:215], v[216:217], 0, s[56:57]
	s_addc_u32 s7, s7, 0
	s_add_i32 s24, s27, s90
	global_load_lds_dwordx4 v[214:215], off
	v_lshl_add_u64 v[214:215], s[6:7], 0, v[130:131]
	s_mov_b32 m0, s24
	s_nop 0
	global_load_lds_dwordx4 v[214:215], off
	v_lshl_add_u64 v[214:215], s[6:7], 0, v[134:135]
	s_add_i32 m0, s24, 0x2000
	s_nop 0
	global_load_lds_dwordx4 v[214:215], off
	v_lshl_add_u64 v[214:215], v[218:219], 0, s[56:57]
	s_mov_b32 m0, s97
	s_nop 0
	global_load_lds_dwordx4 v[214:215], off
	v_lshl_add_u64 v[214:215], v[220:221], 0, s[56:57]
	s_mov_b32 m0, s9
	s_nop 0
	global_load_lds_dwordx4 v[214:215], off
	s_waitcnt vmcnt(8)
	s_waitcnt lgkmcnt(0)
	s_barrier
	s_setprio 1
	s_waitcnt lgkmcnt(0)
	v_mfma_f32_16x16x32_bf16 v[60:63], v[150:153], v[182:185], v[60:63]
	v_mfma_f32_16x16x32_bf16 v[56:59], v[158:161], v[182:185], v[56:59]
	v_mfma_f32_16x16x32_bf16 v[44:47], v[150:153], v[190:193], v[44:47]
	v_mfma_f32_16x16x32_bf16 v[40:43], v[158:161], v[190:193], v[40:43]
	v_mfma_f32_16x16x32_bf16 v[28:31], v[150:153], v[198:201], v[28:31]
	v_mfma_f32_16x16x32_bf16 v[24:27], v[158:161], v[198:201], v[24:27]
	v_mfma_f32_16x16x32_bf16 v[12:15], v[150:153], v[206:209], v[12:15]
	v_mfma_f32_16x16x32_bf16 v[8:11], v[158:161], v[206:209], v[8:11]
	v_mfma_f32_16x16x32_bf16 v[60:63], v[154:157], v[186:189], v[60:63]
	v_mfma_f32_16x16x32_bf16 v[56:59], v[162:165], v[186:189], v[56:59]
	v_mfma_f32_16x16x32_bf16 v[44:47], v[154:157], v[194:197], v[44:47]
	v_mfma_f32_16x16x32_bf16 v[40:43], v[162:165], v[194:197], v[40:43]
	v_mfma_f32_16x16x32_bf16 v[28:31], v[154:157], v[202:205], v[28:31]
	v_mfma_f32_16x16x32_bf16 v[24:27], v[162:165], v[202:205], v[24:27]
	v_mfma_f32_16x16x32_bf16 v[12:15], v[154:157], v[210:213], v[12:15]
	v_mfma_f32_16x16x32_bf16 v[8:11], v[162:165], v[210:213], v[8:11]
	s_setprio 0
	s_setprio 1
	v_mfma_f32_16x16x32_bf16 v[52:55], v[166:169], v[182:185], v[52:55]
	v_mfma_f32_16x16x32_bf16 v[48:51], v[174:177], v[182:185], v[48:51]
	v_mfma_f32_16x16x32_bf16 v[36:39], v[166:169], v[190:193], v[36:39]
	v_mfma_f32_16x16x32_bf16 v[32:35], v[174:177], v[190:193], v[32:35]
	v_mfma_f32_16x16x32_bf16 v[20:23], v[166:169], v[198:201], v[20:23]
	v_mfma_f32_16x16x32_bf16 v[16:19], v[174:177], v[198:201], v[16:19]
	v_mfma_f32_16x16x32_bf16 v[4:7], v[166:169], v[206:209], v[4:7]
	v_mfma_f32_16x16x32_bf16 v[0:3], v[174:177], v[206:209], v[0:3]
	v_mfma_f32_16x16x32_bf16 v[52:55], v[170:173], v[186:189], v[52:55]
	v_mfma_f32_16x16x32_bf16 v[48:51], v[178:181], v[186:189], v[48:51]
	v_mfma_f32_16x16x32_bf16 v[36:39], v[170:173], v[194:197], v[36:39]
	v_mfma_f32_16x16x32_bf16 v[32:35], v[178:181], v[194:197], v[32:35]
	v_mfma_f32_16x16x32_bf16 v[20:23], v[170:173], v[202:205], v[20:23]
	v_mfma_f32_16x16x32_bf16 v[16:19], v[178:181], v[202:205], v[16:19]
	v_mfma_f32_16x16x32_bf16 v[4:7], v[170:173], v[210:213], v[4:7]
	v_mfma_f32_16x16x32_bf16 v[0:3], v[178:181], v[210:213], v[0:3]
	s_setprio 0
	s_barrier
	s_cmp_gt_u32 s23, 13
	s_mov_b32 s23, s52
	s_cbranch_scc1 .LBB0_499
	s_branch .LBB0_493

; #define PG8_STAGE(bufoff, gbase, voff) do { _Pragma("unroll") for (int _i = 0; _i < 2; ++_i) \
;         __builtin_amdgcn_global_load_lds((const unsigned*)((const char*)(gbase) + (voff)[_i]), (PG8_LAS unsigned*)(lds + (bufoff) + ldsw + _i * 8192), 16, 0, 0); } while (0)
; #define PG8_WAIT_V(n) asm volatile("s_waitcnt vmcnt(" #n ")" ::: "memory")
; #define PG8_BAR __builtin_amdgcn_s_barrier()
; template <class Epi, class Sched, bool ALIGN_EPI = false, bool SP2 = false>
; __device__ __forceinline__ void gemm_phase(PG8_LAS unsigned char* lds, const Gemm g, const Sched& S, const Epi& E) {
;     ...
;     if constexpr (SP2) {
;         PG8_STAGE(PG8_SB(0, 0), cB, voffB); PG8_STAGE(PG8_SB(0, 1), cB + hstepB, voffB); PG8_STAGE(PG8_SA(0, 0), cA, voffA); PG8_STAGE(PG8_SA(0, 1), cA + hstepA, voffA);
;         if (wr == 1) PG8_BAR;
;         PG8_WAIT_V(2); PG8_BAR;
;         PG8_STAGE(PG8_SB(1, 0), cB + kstep, voffB); PG8_STAGE(PG8_SA(1, 0), cA + kstepA, voffA); PG8_STAGE(PG8_SB(1, 1), cB + hstepB + kstep, voffB);
;         PG8_WAIT_V(6); PG8_BAR;
.LBB0_1189:
	s_add_i32 s67, s8, 0x18000
	s_mov_b64 s[24:25], 0x80
	s_and_b32 s1, s2, 3
	v_lshl_add_u64 v[6:7], v[6:7], 0, s[24:25]
	s_mov_b32 m0, s67
	s_add_i32 s76, s8, 0x1a000
	s_lshl_b32 s3, s0, 13
	s_lshl_b32 s66, s1, 5
	s_lshl_b32 s1, s1, 12
	s_waitcnt vmcnt(2)
	s_barrier
	global_load_lds_dwordx4 v[6:7], off
	v_lshl_add_u64 v[4:5], v[4:5], 0, s[24:25]
	s_mov_b32 m0, s76
	s_add_i32 s77, s8, 0x8000
	s_add_i32 s78, s8, 0xa000
	global_load_lds_dwordx4 v[4:5], off
	v_lshl_add_u64 v[0:1], v[0:1], 0, s[24:25]
	s_mov_b32 m0, s77
	s_add_u32 s6, s52, 0x40080
	global_load_lds_dwordx4 v[0:1], off
	v_lshl_add_u64 v[0:1], v[2:3], 0, s[24:25]
	s_mov_b32 m0, s78
	s_addc_u32 s7, s53, 0
	s_add_i32 s79, s8, 0x1c000
	global_load_lds_dwordx4 v[0:1], off
	v_lshl_add_u64 v[0:1], s[6:7], 0, v[194:195]
	s_mov_b32 m0, s79
	s_add_i32 s80, s8, 0x1e000
	global_load_lds_dwordx4 v[0:1], off
	v_lshl_add_u64 v[0:1], s[6:7], 0, v[198:199]
	s_mov_b32 m0, s80
	s_cmpk_lt_u32 s18, 0x100
	global_load_lds_dwordx4 v[0:1], off
	v_lshrrev_b32_e32 v0, 1, v8
	v_and_b32_e32 v0, 24, v0
	v_and_b32_e32 v1, 15, v8
	v_lshlrev_b32_e32 v2, 1, v0
	v_lshl_or_b32 v210, s0, 6, v1
	v_lshl_or_b32 v1, v1, 6, v2
	v_lshlrev_b32_e32 v2, 2, v8
	v_and_b32_e32 v2, 32, v2
	s_waitcnt vmcnt(0)
	s_cselect_b64 s[26:27], -1, 0
	s_lshl_b32 s2, s2, 13
	v_bitop3_b32 v3, v1, s3, v2 bitop3:0xde
	v_bitop3_b32 v1, v1, s1, v2 bitop3:0xde
	s_and_b32 s2, s2, 0x2000
	v_cmp_gt_u32_e64 s[0:1], 64, v238
	v_mov_b32_e32 v211, 0x358637bd
	s_lshl_b32 s81, s2, 1
	v_lshlrev_b32_e32 v200, 1, v0
	v_add_u32_e32 v212, 0, v1
	v_add_u32_e32 v213, 0, v3
	s_mov_b32 s82, 0
	s_barrier
	s_branch .LBB0_1192

;     __host__ __device__ __forceinline__ bool next(int i, Unit& u) const { const long L = (long)i * G + c; if (L >= nwg) return false; map((int)L, u); return true; }
; #define PG8_STAGE(bufoff, gbase, voff) do { _Pragma("unroll") for (int _i = 0; _i < 2; ++_i) \
;         __builtin_amdgcn_global_load_lds((const unsigned*)((const char*)(gbase) + (voff)[_i]), (PG8_LAS unsigned*)(lds + (bufoff) + ldsw + _i * 8192), 16, 0, 0); } while (0)
; #define PG8_WAIT_V(n) asm volatile("s_waitcnt vmcnt(" #n ")" ::: "memory")
; #define PG8_WAIT_L(n) asm volatile("s_waitcnt lgkmcnt(" #n ")" ::: "memory")
;     __host__ __device__ __forceinline__ bool next(int i, Unit& u) const {
;         const int L = i * sp_.G + sp_.c; const bool isp = L < sp_.nwg; const int j = isp ? 0 : L - sp_.nwg;
;         Unit a; sp_.map(isp ? L : 0, a);
;         const int s = j >> 2;
;         u.pm = isp ? a.pm : 64 + s / sp_.nN; u.pn = isp ? a.pn : s % sp_.nN; u.k0 = 0; u.nt = a.nt; u.sp = -1; u.qa = isp ? -1 : ((j >> 1) & 1); u.qb = isp ? -1 : (j & 1);
;         return isp || j < nq;
; template <class Epi, class Sched, bool ALIGN_EPI = false, bool SP2 = false>
; __device__ __forceinline__ void gemm_phase(PG8_LAS unsigned char* lds, const Gemm g, const Sched& S, const Epi& E) {
;     ...
;         const bool has_next = S.next(ui + 1, nxt);
;         const char* nA = has_next ? (const char*)g.A + (size_t)nxt.pm * tstepA + (size_t)(nxt.k0 >> 6) * kstepA + (nxt.qa > 0 ? hstepA : (size_t)0) : cA; const char* nB = has_next ? (const char*)g.Bt + (size_t)nxt.pn * tstepB + (size_t)nxt.k0 * 2 + (nxt.qb > 0 ? hstepB : (size_t)0) : cB;
;         const bool whole = cur.qa < 0;
;         const int nt = cur.nt;
;         for (int t = 0; t < nt; t += 2) {
;             const bool last = (t == nt - 2);
;             const char* a1 = cA + (size_t)(t + 1) * kstepA;
;             const char* a2 = last ? nA : cA + (size_t)(t + 2) * kstepA; const char* b2 = last ? nB : cB + (size_t)(t + 2) * kstep;
;             const char* a3 = a2 + kstepA; const char* b3 = b2 + kstep;
;             if (last && has_next) S.a_ready(nxt);
;             if constexpr (SP2) {
;             PG8_LDB(B0, 0, 0); PG8_LDB(B1, 0, 1); PG8_SCHED; PG8_LDA(At, 0, 0); PG8_STAGE(PG8_SA(1, 1), a1 + hstepA, voffA);
;             PG8_WAIT_V(8); PG8_WAIT_L(0); PG8_BAR; PG8_MMA(0, 0, At, B0); if (whole) PG8_MMA(0, 1, At, B1); PG8_BAR; PG8_SCHED;
.LBB0_1200:
	s_bfe_u32 s29, s28, 0x10001
	s_and_b64 s[6:7], s[2:3], exec
	s_cselect_b32 s83, -1, s29
	s_and_b32 s18, s18, 1
	s_and_b64 s[6:7], s[2:3], exec
	s_cselect_b32 s84, -1, s18
	s_cmpk_lt_u32 s28, 0x100
	s_cselect_b64 s[6:7], -1, 0
	s_ashr_i32 s39, s38, 31
	s_or_b64 s[42:43], s[2:3], s[6:7]
	s_lshl_b64 s[2:3], s[38:39], 19
	s_add_u32 s2, s30, s2
	s_addc_u32 s3, s31, s3
	s_cmp_gt_i32 s83, 0
	s_cselect_b32 s6, 0x40000, 0
	s_add_u32 s40, s2, s6
	s_addc_u32 s41, s3, 0
	s_and_b64 s[2:3], s[42:43], exec
	s_cselect_b32 s39, s41, s51
	s_cselect_b32 s47, s40, s50
	s_ashr_i32 s37, s36, 31
	s_lshl_b64 s[2:3], s[36:37], 19
	s_add_u32 s2, s22, s2
	s_addc_u32 s3, s23, s3
	s_cmp_gt_i32 s84, 0
	s_cselect_b32 s6, 0x40000, 0
	s_add_u32 s44, s2, s6
	s_addc_u32 s45, s3, 0
	s_and_b64 s[2:3], s[42:43], exec
	s_cselect_b32 s37, s45, s53
	s_cselect_b32 s90, s44, s52
	s_cmp_lt_i32 s86, 0
	s_cselect_b64 s[54:55], -1, 0
	s_cmp_gt_i32 s38, 63
	s_mov_b32 s87, 0
	s_cselect_b64 s[56:57], -1, 0
	s_mov_b64 s[6:7], 0
	v_add_u32_e32 v128, 0x10000, v212
	v_add_u32_e32 v140, 0x14000, v212
	ds_read_b128 v[144:147], v128
	ds_read_b128 v[148:151], v128 offset:1024
	ds_read_b128 v[152:155], v128 offset:2048
	ds_read_b128 v[156:159], v128 offset:3072
	ds_read_b128 v[128:131], v140
	ds_read_b128 v[132:135], v140 offset:1024
	ds_read_b128 v[136:139], v140 offset:2048
	ds_read_b128 v[140:143], v140 offset:3072
	s_or_b32 s18, s87, 1
	s_lshl_b64 s[2:3], s[18:19], 7
	s_add_u32 s2, s50, s2
	s_addc_u32 s3, s51, s3
	s_add_u32 s2, s2, 0x40000
	s_addc_u32 s3, s3, 0
	v_lshl_add_u64 v[202:203], s[2:3], 0, v[192:193]
	s_add_i32 m0, s8, 0xc000
	s_waitcnt lgkmcnt(0)
	ds_read_b128 v[184:187], v213
	ds_read_b128 v[188:191], v213 offset:1024
	ds_read_b128 v[176:179], v213 offset:2048
	ds_read_b128 v[180:183], v213 offset:3072
	ds_read_b128 v[168:171], v213 offset:4096
	ds_read_b128 v[172:175], v213 offset:5120
	ds_read_b128 v[160:163], v213 offset:6144
	ds_read_b128 v[164:167], v213 offset:7168
	global_load_lds_dwordx4 v[202:203], off
	v_lshl_add_u64 v[202:203], s[2:3], 0, v[196:197]
	s_add_i32 m0, s8, 0xe000
	s_nop 0
	global_load_lds_dwordx4 v[202:203], off
	s_waitcnt vmcnt(16)
	s_waitcnt lgkmcnt(0)
	s_barrier
	s_setprio 1
	s_waitcnt lgkmcnt(0)
	v_mfma_f32_16x16x32_bf16 v[124:127], v[144:147], v[184:187], 0
	v_mfma_f32_16x16x32_bf16 v[120:123], v[152:155], v[184:187], 0
	v_mfma_f32_16x16x32_bf16 v[116:119], v[144:147], v[176:179], 0
	v_mfma_f32_16x16x32_bf16 v[112:115], v[152:155], v[176:179], 0
	v_mfma_f32_16x16x32_bf16 v[108:111], v[144:147], v[168:171], 0
	v_mfma_f32_16x16x32_bf16 v[104:107], v[152:155], v[168:171], 0
	v_mfma_f32_16x16x32_bf16 v[100:103], v[144:147], v[160:163], 0
	v_mfma_f32_16x16x32_bf16 v[88:91], v[152:155], v[160:163], 0
	v_mfma_f32_16x16x32_bf16 v[124:127], v[148:151], v[188:191], v[124:127]
	v_mfma_f32_16x16x32_bf16 v[120:123], v[156:159], v[188:191], v[120:123]
	v_mfma_f32_16x16x32_bf16 v[116:119], v[148:151], v[180:183], v[116:119]
	v_mfma_f32_16x16x32_bf16 v[112:115], v[156:159], v[180:183], v[112:115]
	v_mfma_f32_16x16x32_bf16 v[108:111], v[148:151], v[172:175], v[108:111]
	v_mfma_f32_16x16x32_bf16 v[104:107], v[156:159], v[172:175], v[104:107]
	v_mfma_f32_16x16x32_bf16 v[100:103], v[148:151], v[164:167], v[100:103]
	v_mfma_f32_16x16x32_bf16 v[88:91], v[156:159], v[164:167], v[88:91]
	s_setprio 0
	v_cndmask_b32_e64 v202, 0, 1, s[54:55]
	v_cmp_ne_u32_e64 s[2:3], 1, v202
	s_andn2_b64 vcc, exec, s[54:55]
	s_cbranch_vccnz .Lpk_up1_1211
	s_setprio 1
	v_mfma_f32_16x16x32_bf16 v[96:99], v[128:131], v[184:187], 0
	v_mfma_f32_16x16x32_bf16 v[92:95], v[136:139], v[184:187], 0
	v_mfma_f32_16x16x32_bf16 v[84:87], v[128:131], v[176:179], 0
	v_mfma_f32_16x16x32_bf16 v[80:83], v[136:139], v[176:179], 0
	v_mfma_f32_16x16x32_bf16 v[76:79], v[128:131], v[168:171], 0
	v_mfma_f32_16x16x32_bf16 v[72:75], v[136:139], v[168:171], 0
	v_mfma_f32_16x16x32_bf16 v[68:71], v[128:131], v[160:163], 0
	v_mfma_f32_16x16x32_bf16 v[64:67], v[136:139], v[160:163], 0
	v_mfma_f32_16x16x32_bf16 v[96:99], v[132:135], v[188:191], v[96:99]
	v_mfma_f32_16x16x32_bf16 v[92:95], v[140:143], v[188:191], v[92:95]
	v_mfma_f32_16x16x32_bf16 v[84:87], v[132:135], v[180:183], v[84:87]
	v_mfma_f32_16x16x32_bf16 v[80:83], v[140:143], v[180:183], v[80:83]
	v_mfma_f32_16x16x32_bf16 v[76:79], v[132:135], v[172:175], v[76:79]
	v_mfma_f32_16x16x32_bf16 v[72:75], v[140:143], v[172:175], v[72:75]
	v_mfma_f32_16x16x32_bf16 v[68:71], v[132:135], v[164:167], v[68:71]
	v_mfma_f32_16x16x32_bf16 v[64:67], v[140:143], v[164:167], v[64:67]
	s_setprio 0
; #define PG8_STAGE(bufoff, gbase, voff) do { _Pragma("unroll") for (int _i = 0; _i < 2; ++_i) \
;         __builtin_amdgcn_global_load_lds((const unsigned*)((const char*)(gbase) + (voff)[_i]), (PG8_LAS unsigned*)(lds + (bufoff) + ldsw + _i * 8192), 16, 0, 0); } while (0)
; #define PG8_LDA(dst, b, h) do { _Pragma("unroll") for (int m = 0; m < 4; ++m) _Pragma("unroll") for (int k = 0; k < 2; ++k) dst[m][k] = *(const PG8_LAS bf16x8*)(lds + PG8_SA(b, h) + aoff + m * 2048 + k * 1024); } while (0)
; #define PG8_MMA(ai, bj, At, Bt) do { __builtin_amdgcn_s_setprio(1); _Pragma("unroll") for (int m = 0; m < 4; ++m) _Pragma("unroll") for (int n = 0; n < 2; ++n) _Pragma("unroll") for (int k = 0; k < 2; ++k) \
;         acc[ai][bj][m][n] = __builtin_amdgcn_mfma_f32_16x16x32_bf16(Bt[n][k], At[m][k], acc[ai][bj][m][n], 0, 0, 0); __builtin_amdgcn_s_setprio(0); } while (0)
; #define PG8_WAIT_V(n) asm volatile("s_waitcnt vmcnt(" #n ")" ::: "memory")
; #define PG8_WAIT_L(n) asm volatile("s_waitcnt lgkmcnt(" #n ")" ::: "memory")
; #define PG8_BAR __builtin_amdgcn_s_barrier()
; #define PG8_SCHED __builtin_amdgcn_sched_barrier(0)
; template <class Epi, class Sched, bool ALIGN_EPI = false, bool SP2 = false>
; __device__ __forceinline__ void gemm_phase(PG8_LAS unsigned char* lds, const Gemm g, const Sched& S, const Epi& E) {
;     ...
;             PG8_WAIT_V(8); PG8_WAIT_L(0); PG8_BAR; PG8_MMA(0, 0, At, B0); if (whole) PG8_MMA(0, 1, At, B1); PG8_BAR; PG8_SCHED;
;             PG8_LDA(At, 0, 1); PG8_STAGE(PG8_SB(0, 0), b2, voffB); PG8_STAGE(PG8_SB(0, 1), b2 + hstepB, voffB); PG8_STAGE(PG8_SA(0, 0), a2, voffA);
;             PG8_WAIT_V(8); PG8_WAIT_L(0); PG8_BAR; if (whole) { PG8_MMA(1, 0, At, B0); PG8_MMA(1, 1, At, B1); } PG8_BAR; PG8_SCHED;
.Lpk_up1_1211:
	s_add_i32 s18, s87, 2
	s_lshl_b64 s[28:29], s[18:19], 7
	s_add_u32 s91, s50, s28
	s_addc_u32 s92, s51, s29
	s_and_b64 s[58:59], s[6:7], exec
	s_cselect_b32 s59, s39, s92
	s_cselect_b32 s58, s47, s91
	s_add_u32 s28, s52, s28
	s_addc_u32 s29, s53, s29
	s_and_b64 s[6:7], s[6:7], exec
	s_cselect_b32 s7, s37, s29
	s_cselect_b32 s6, s90, s28
	s_barrier
	s_mov_b32 m0, s9
	v_lshl_add_u64 v[202:203], s[6:7], 0, v[194:195]
	s_add_u32 s28, s6, 0x40000
	ds_read_b128 v[184:187], v213 offset:16384
	ds_read_b128 v[188:191], v213 offset:17408
	ds_read_b128 v[176:179], v213 offset:18432
	ds_read_b128 v[180:183], v213 offset:19456
	ds_read_b128 v[168:171], v213 offset:20480
	ds_read_b128 v[172:175], v213 offset:21504
	ds_read_b128 v[160:163], v213 offset:22528
	ds_read_b128 v[164:167], v213 offset:23552
	global_load_lds_dwordx4 v[202:203], off
	v_lshl_add_u64 v[204:205], s[6:7], 0, v[198:199]
	s_mov_b32 m0, s49
	s_addc_u32 s29, s7, 0
	global_load_lds_dwordx4 v[204:205], off
	v_lshl_add_u64 v[206:207], s[28:29], 0, v[194:195]
	s_mov_b32 m0, s60
	v_lshl_add_u64 v[208:209], s[58:59], 0, v[196:197]
	global_load_lds_dwordx4 v[206:207], off
	v_lshl_add_u64 v[206:207], s[28:29], 0, v[198:199]
	s_mov_b32 m0, s61
	s_and_b64 vcc, exec, s[2:3]
	global_load_lds_dwordx4 v[206:207], off
	v_lshl_add_u64 v[206:207], s[58:59], 0, v[192:193]
	s_mov_b32 m0, s8
	s_nop 0
	global_load_lds_dwordx4 v[206:207], off
	s_mov_b32 m0, s62
	s_nop 0
	global_load_lds_dwordx4 v[208:209], off
	s_waitcnt vmcnt(16)
	s_waitcnt lgkmcnt(0)
	s_barrier
	s_cbranch_vccnz .Lpk_up1_1213
	s_setprio 1
	s_waitcnt lgkmcnt(0)
	v_mfma_f32_16x16x32_bf16 v[60:63], v[144:147], v[184:187], 0
	v_mfma_f32_16x16x32_bf16 v[56:59], v[152:155], v[184:187], 0
	v_mfma_f32_16x16x32_bf16 v[44:47], v[144:147], v[176:179], 0
	v_mfma_f32_16x16x32_bf16 v[40:43], v[152:155], v[176:179], 0
	v_mfma_f32_16x16x32_bf16 v[28:31], v[144:147], v[168:171], 0
	v_mfma_f32_16x16x32_bf16 v[24:27], v[152:155], v[168:171], 0
	v_mfma_f32_16x16x32_bf16 v[12:15], v[144:147], v[160:163], 0
	v_mfma_f32_16x16x32_bf16 v[8:11], v[152:155], v[160:163], 0
	v_mfma_f32_16x16x32_bf16 v[60:63], v[148:151], v[188:191], v[60:63]
	v_mfma_f32_16x16x32_bf16 v[56:59], v[156:159], v[188:191], v[56:59]
	v_mfma_f32_16x16x32_bf16 v[44:47], v[148:151], v[180:183], v[44:47]
	v_mfma_f32_16x16x32_bf16 v[40:43], v[156:159], v[180:183], v[40:43]
	v_mfma_f32_16x16x32_bf16 v[28:31], v[148:151], v[172:175], v[28:31]
	v_mfma_f32_16x16x32_bf16 v[24:27], v[156:159], v[172:175], v[24:27]
	v_mfma_f32_16x16x32_bf16 v[12:15], v[148:151], v[164:167], v[12:15]
	v_mfma_f32_16x16x32_bf16 v[8:11], v[156:159], v[164:167], v[8:11]
	s_setprio 0
	s_setprio 1
	v_mfma_f32_16x16x32_bf16 v[52:55], v[128:131], v[184:187], 0
	v_mfma_f32_16x16x32_bf16 v[48:51], v[136:139], v[184:187], 0
	v_mfma_f32_16x16x32_bf16 v[36:39], v[128:131], v[176:179], 0
	v_mfma_f32_16x16x32_bf16 v[32:35], v[136:139], v[176:179], 0
	v_mfma_f32_16x16x32_bf16 v[20:23], v[128:131], v[168:171], 0
	v_mfma_f32_16x16x32_bf16 v[16:19], v[136:139], v[168:171], 0
	v_mfma_f32_16x16x32_bf16 v[4:7], v[128:131], v[160:163], 0
	v_mfma_f32_16x16x32_bf16 v[0:3], v[136:139], v[160:163], 0
	v_mfma_f32_16x16x32_bf16 v[52:55], v[132:135], v[188:191], v[52:55]
	v_mfma_f32_16x16x32_bf16 v[48:51], v[140:143], v[188:191], v[48:51]
	v_mfma_f32_16x16x32_bf16 v[36:39], v[132:135], v[180:183], v[36:39]
	v_mfma_f32_16x16x32_bf16 v[32:35], v[140:143], v[180:183], v[32:35]
	v_mfma_f32_16x16x32_bf16 v[20:23], v[132:135], v[172:175], v[20:23]
	v_mfma_f32_16x16x32_bf16 v[16:19], v[140:143], v[172:175], v[16:19]
	v_mfma_f32_16x16x32_bf16 v[4:7], v[132:135], v[164:167], v[4:7]
	v_mfma_f32_16x16x32_bf16 v[0:3], v[140:143], v[164:167], v[0:3]
	s_setprio 0

;     __device__ __forceinline__ void a_ready(const Unit& u) const {
;         if (u.pm < 64) return;
;         if (threadIdx.x < 64) {
;             unsigned spins = 0;
;             while ((unsigned)__builtin_amdgcn_readfirstlane(__hip_atomic_load(cnt, __ATOMIC_RELAXED, __HIP_MEMORY_SCOPE_AGENT)) < need && ++spins < (1u << 22)) __builtin_amdgcn_s_sleep(2);
; template <class Epi, class Sched, bool ALIGN_EPI = false, bool SP2 = false>
; __device__ __forceinline__ void gemm_phase(PG8_LAS unsigned char* lds, const Gemm g, const Sched& S, const Epi& E) {
;     ...
;         for (int t = 0; t < nt; t += 2) {
;             const bool last = (t == nt - 2);
;             const char* a1 = cA + (size_t)(t + 1) * kstepA;
;             const char* a2 = last ? nA : cA + (size_t)(t + 2) * kstepA; const char* b2 = last ? nB : cB + (size_t)(t + 2) * kstep;
;             const char* a3 = a2 + kstepA; const char* b3 = b2 + kstep;
;             if (last && has_next) S.a_ready(nxt);
.Lpk_up1_1217:
	s_barrier
	s_cmp_gt_u32 s87, 13
	s_cbranch_scc1 .LBB0_1219
	s_mov_b32 s87, s18
	s_branch .LBB0_1201
.LBB0_1201:
	s_cmp_eq_u32 s87, 14
	s_cselect_b64 s[6:7], -1, 0
	s_and_b64 s[2:3], s[42:43], s[6:7]
	s_and_b64 s[2:3], s[2:3], s[56:57]
	s_andn2_b64 vcc, exec, s[2:3]
	s_cbranch_vccnz .LBB0_1209
	s_and_saveexec_b64 s[2:3], s[0:1]
	s_cbranch_execz .LBB0_1208
	v_mov_b32_e32 v128, 0x3fffff
	s_branch .LBB0_1205
